# plus chunkprep forward substitution: right-hand sides be*Kf of a pass read from LDS up front (32 reads, one wait) instead of inside the dependent chain
# speedup vs baseline: 1.0058x; 1.0057x over previous
; __device__ __forceinline__ unsigned pk2n(float lo, float hi) { return __builtin_bit_cast(unsigned, __builtin_convertvector((f32x2){lo, hi}, bf16v2)); }
; __device__ __forceinline__ void chunkprep_phase(const Params& P, LAS unsigned char* lds) {
;     ...
;         for (int pass = 0; pass < 3; ++pass) {
;             if (pass < 2 || lane < 16) {
;                 const int col = (pass & 1) * 64 + lane;
;                 float x[16];
; #pragma unroll
;                 for (int tt = 0; tt < 16; ++tt) {
;                     float acc = (pass < 2) ? be[tt] * Kf[tt * 132 + col] : ((tt == lane) ? 1.f : 0.f);
; #pragma unroll
;                     for (int s = 0; s < tt; ++s) acc -= Am[tt * 16 + s] * x[s];
;                     x[tt] = acc;
;                     if (pass < 2) Wb[tt * 136 + col] = (bf16_t)(pk2n(acc, 0.f) & 0xffffu); else Tt[tt * 17 + lane] = acc; }
.LBB0_463:
	s_cmpk_lg_i32 s37, 0x80
	s_cselect_b64 s[26:27], -1, 0
	s_cmpk_eq_i32 s37, 0x80
	s_cselect_b64 s[46:47], -1, 0
	s_or_b64 s[24:25], s[4:5], s[26:27]
	s_and_saveexec_b64 s[82:83], s[24:25]
	s_cbranch_execz .LBB0_462
	v_and_or_b32 v1, s37, 64, v90
	v_cndmask_b32_e64 v2, 0, 1, s[26:27]
	v_lshl_add_u32 v12, v1, 2, v92
	v_cmp_ne_u32_e64 s[24:25], 1, v2
	s_andn2_b64 vcc, exec, s[26:27]
	v_mov_b32_e32 v2, v103
	s_cbranch_vccnz .LBB0_466
	ds_read_b32 v142, v92 offset:16000
	ds_read_b32 v143, v92 offset:16004
	ds_read_b32 v144, v92 offset:16008
	ds_read_b32 v145, v92 offset:16012
	ds_read_b32 v146, v92 offset:16016
	ds_read_b32 v147, v92 offset:16020
	ds_read_b32 v148, v92 offset:16024
	ds_read_b32 v149, v92 offset:16028
	ds_read_b32 v150, v92 offset:16032
	ds_read_b32 v151, v92 offset:16036
	ds_read_b32 v152, v92 offset:16040
	ds_read_b32 v153, v92 offset:16044
	ds_read_b32 v154, v92 offset:16048
	ds_read_b32 v155, v92 offset:16052
	ds_read_b32 v156, v92 offset:16056
	ds_read_b32 v157, v92 offset:16060
	ds_read_b32 v158, v12
	ds_read_b32 v159, v12 offset:528
	ds_read_b32 v160, v12 offset:1056
	ds_read_b32 v161, v12 offset:1584
	ds_read_b32 v162, v12 offset:2112
	ds_read_b32 v163, v12 offset:2640
	ds_read_b32 v164, v12 offset:3168
	ds_read_b32 v165, v12 offset:3696
	ds_read_b32 v166, v12 offset:4224
	ds_read_b32 v167, v12 offset:4752
	ds_read_b32 v168, v12 offset:5280
	ds_read_b32 v169, v12 offset:5808
	ds_read_b32 v170, v12 offset:6336
	ds_read_b32 v171, v12 offset:6864
	ds_read_b32 v172, v12 offset:7392
	ds_read_b32 v173, v12 offset:7920
	s_waitcnt lgkmcnt(0)
	v_mul_f32_e32 v142, v142, v158
	v_mul_f32_e32 v143, v143, v159
	v_mul_f32_e32 v144, v144, v160
	v_mul_f32_e32 v145, v145, v161
	v_mul_f32_e32 v146, v146, v162
	v_mul_f32_e32 v147, v147, v163
	v_mul_f32_e32 v148, v148, v164
	v_mul_f32_e32 v149, v149, v165
	v_mul_f32_e32 v150, v150, v166
	v_mul_f32_e32 v151, v151, v167
	v_mul_f32_e32 v152, v152, v168
	v_mul_f32_e32 v153, v153, v169
	v_mul_f32_e32 v154, v154, v170
	v_mul_f32_e32 v155, v155, v171
	v_mul_f32_e32 v156, v156, v172
	v_mul_f32_e32 v157, v157, v173
	v_mov_b32_e32 v2, v142

; __device__ __forceinline__ unsigned pk2n(float lo, float hi) { return __builtin_bit_cast(unsigned, __builtin_convertvector((f32x2){lo, hi}, bf16v2)); }
; __device__ __forceinline__ void chunkprep_phase(const Params& P, LAS unsigned char* lds) {
;     ...
;                 for (int tt = 0; tt < 16; ++tt) {
;                     float acc = (pass < 2) ? be[tt] * Kf[tt * 132 + col] : ((tt == lane) ? 1.f : 0.f);
; #pragma unroll
;                     for (int s = 0; s < tt; ++s) acc -= Am[tt * 16 + s] * x[s];
;                     x[tt] = acc;
;                     if (pass < 2) Wb[tt * 136 + col] = (bf16_t)(pk2n(acc, 0.f) & 0xffffu); else Tt[tt * 17 + lane] = acc; }
.LBB0_470:
	s_and_b64 vcc, exec, s[24:25]
	v_mov_b32_e32 v13, v104
	s_cbranch_vccnz .LBB0_472
	v_mov_b32_e32 v13, v143

; __device__ __forceinline__ unsigned pk2n(float lo, float hi) { return __builtin_bit_cast(unsigned, __builtin_convertvector((f32x2){lo, hi}, bf16v2)); }
; __device__ __forceinline__ void chunkprep_phase(const Params& P, LAS unsigned char* lds) {
;     ...
;                 for (int tt = 0; tt < 16; ++tt) {
;                     float acc = (pass < 2) ? be[tt] * Kf[tt * 132 + col] : ((tt == lane) ? 1.f : 0.f);
; #pragma unroll
;                     for (int s = 0; s < tt; ++s) acc -= Am[tt * 16 + s] * x[s];
;                     x[tt] = acc;
;                     if (pass < 2) Wb[tt * 136 + col] = (bf16_t)(pk2n(acc, 0.f) & 0xffffu); else Tt[tt * 17 + lane] = acc; }
.LBB0_475:
	v_mov_b32_e32 v14, v144

; __device__ __forceinline__ unsigned pk2n(float lo, float hi) { return __builtin_bit_cast(unsigned, __builtin_convertvector((f32x2){lo, hi}, bf16v2)); }
; __device__ __forceinline__ void chunkprep_phase(const Params& P, LAS unsigned char* lds) {
;     ...
;                 for (int tt = 0; tt < 16; ++tt) {
;                     float acc = (pass < 2) ? be[tt] * Kf[tt * 132 + col] : ((tt == lane) ? 1.f : 0.f);
; #pragma unroll
;                     for (int s = 0; s < tt; ++s) acc -= Am[tt * 16 + s] * x[s];
;                     x[tt] = acc;
;                     if (pass < 2) Wb[tt * 136 + col] = (bf16_t)(pk2n(acc, 0.f) & 0xffffu); else Tt[tt * 17 + lane] = acc; }
.LBB0_479:
	v_mov_b32_e32 v15, v145

; __device__ __forceinline__ unsigned pk2n(float lo, float hi) { return __builtin_bit_cast(unsigned, __builtin_convertvector((f32x2){lo, hi}, bf16v2)); }
; __device__ __forceinline__ void chunkprep_phase(const Params& P, LAS unsigned char* lds) {
;     ...
;                 for (int tt = 0; tt < 16; ++tt) {
;                     float acc = (pass < 2) ? be[tt] * Kf[tt * 132 + col] : ((tt == lane) ? 1.f : 0.f);
; #pragma unroll
;                     for (int s = 0; s < tt; ++s) acc -= Am[tt * 16 + s] * x[s];
;                     x[tt] = acc;
;                     if (pass < 2) Wb[tt * 136 + col] = (bf16_t)(pk2n(acc, 0.f) & 0xffffu); else Tt[tt * 17 + lane] = acc; }
.LBB0_483:
	v_mov_b32_e32 v16, v146

; __device__ __forceinline__ unsigned pk2n(float lo, float hi) { return __builtin_bit_cast(unsigned, __builtin_convertvector((f32x2){lo, hi}, bf16v2)); }
; __device__ __forceinline__ void chunkprep_phase(const Params& P, LAS unsigned char* lds) {
;     ...
;                 for (int tt = 0; tt < 16; ++tt) {
;                     float acc = (pass < 2) ? be[tt] * Kf[tt * 132 + col] : ((tt == lane) ? 1.f : 0.f);
; #pragma unroll
;                     for (int s = 0; s < tt; ++s) acc -= Am[tt * 16 + s] * x[s];
;                     x[tt] = acc;
;                     if (pass < 2) Wb[tt * 136 + col] = (bf16_t)(pk2n(acc, 0.f) & 0xffffu); else Tt[tt * 17 + lane] = acc; }
.LBB0_487:
	v_mov_b32_e32 v17, v147

; __device__ __forceinline__ unsigned pk2n(float lo, float hi) { return __builtin_bit_cast(unsigned, __builtin_convertvector((f32x2){lo, hi}, bf16v2)); }
; __device__ __forceinline__ void chunkprep_phase(const Params& P, LAS unsigned char* lds) {
;     ...
;                 for (int tt = 0; tt < 16; ++tt) {
;                     float acc = (pass < 2) ? be[tt] * Kf[tt * 132 + col] : ((tt == lane) ? 1.f : 0.f);
; #pragma unroll
;                     for (int s = 0; s < tt; ++s) acc -= Am[tt * 16 + s] * x[s];
;                     x[tt] = acc;
;                     if (pass < 2) Wb[tt * 136 + col] = (bf16_t)(pk2n(acc, 0.f) & 0xffffu); else Tt[tt * 17 + lane] = acc; }
.LBB0_491:
	v_mov_b32_e32 v18, v148

; __device__ __forceinline__ unsigned pk2n(float lo, float hi) { return __builtin_bit_cast(unsigned, __builtin_convertvector((f32x2){lo, hi}, bf16v2)); }
; __device__ __forceinline__ void chunkprep_phase(const Params& P, LAS unsigned char* lds) {
;     ...
;                 for (int tt = 0; tt < 16; ++tt) {
;                     float acc = (pass < 2) ? be[tt] * Kf[tt * 132 + col] : ((tt == lane) ? 1.f : 0.f);
; #pragma unroll
;                     for (int s = 0; s < tt; ++s) acc -= Am[tt * 16 + s] * x[s];
;                     x[tt] = acc;
;                     if (pass < 2) Wb[tt * 136 + col] = (bf16_t)(pk2n(acc, 0.f) & 0xffffu); else Tt[tt * 17 + lane] = acc; }
.LBB0_495:
	v_mov_b32_e32 v19, v149

; __device__ __forceinline__ unsigned pk2n(float lo, float hi) { return __builtin_bit_cast(unsigned, __builtin_convertvector((f32x2){lo, hi}, bf16v2)); }
; __device__ __forceinline__ void chunkprep_phase(const Params& P, LAS unsigned char* lds) {
;     ...
;                 for (int tt = 0; tt < 16; ++tt) {
;                     float acc = (pass < 2) ? be[tt] * Kf[tt * 132 + col] : ((tt == lane) ? 1.f : 0.f);
; #pragma unroll
;                     for (int s = 0; s < tt; ++s) acc -= Am[tt * 16 + s] * x[s];
;                     x[tt] = acc;
;                     if (pass < 2) Wb[tt * 136 + col] = (bf16_t)(pk2n(acc, 0.f) & 0xffffu); else Tt[tt * 17 + lane] = acc; }
.LBB0_499:
	v_mov_b32_e32 v20, v150

; __device__ __forceinline__ unsigned pk2n(float lo, float hi) { return __builtin_bit_cast(unsigned, __builtin_convertvector((f32x2){lo, hi}, bf16v2)); }
; __device__ __forceinline__ void chunkprep_phase(const Params& P, LAS unsigned char* lds) {
;     ...
;                 for (int tt = 0; tt < 16; ++tt) {
;                     float acc = (pass < 2) ? be[tt] * Kf[tt * 132 + col] : ((tt == lane) ? 1.f : 0.f);
; #pragma unroll
;                     for (int s = 0; s < tt; ++s) acc -= Am[tt * 16 + s] * x[s];
;                     x[tt] = acc;
;                     if (pass < 2) Wb[tt * 136 + col] = (bf16_t)(pk2n(acc, 0.f) & 0xffffu); else Tt[tt * 17 + lane] = acc; }
.LBB0_503:
	v_mov_b32_e32 v21, v151

; __device__ __forceinline__ unsigned pk2n(float lo, float hi) { return __builtin_bit_cast(unsigned, __builtin_convertvector((f32x2){lo, hi}, bf16v2)); }
; __device__ __forceinline__ void chunkprep_phase(const Params& P, LAS unsigned char* lds) {
;     ...
;                 for (int tt = 0; tt < 16; ++tt) {
;                     float acc = (pass < 2) ? be[tt] * Kf[tt * 132 + col] : ((tt == lane) ? 1.f : 0.f);
; #pragma unroll
;                     for (int s = 0; s < tt; ++s) acc -= Am[tt * 16 + s] * x[s];
;                     x[tt] = acc;
;                     if (pass < 2) Wb[tt * 136 + col] = (bf16_t)(pk2n(acc, 0.f) & 0xffffu); else Tt[tt * 17 + lane] = acc; }
.LBB0_507:
	v_mov_b32_e32 v22, v152

; __device__ __forceinline__ unsigned pk2n(float lo, float hi) { return __builtin_bit_cast(unsigned, __builtin_convertvector((f32x2){lo, hi}, bf16v2)); }
; __device__ __forceinline__ void chunkprep_phase(const Params& P, LAS unsigned char* lds) {
;     ...
;                 for (int tt = 0; tt < 16; ++tt) {
;                     float acc = (pass < 2) ? be[tt] * Kf[tt * 132 + col] : ((tt == lane) ? 1.f : 0.f);
; #pragma unroll
;                     for (int s = 0; s < tt; ++s) acc -= Am[tt * 16 + s] * x[s];
;                     x[tt] = acc;
;                     if (pass < 2) Wb[tt * 136 + col] = (bf16_t)(pk2n(acc, 0.f) & 0xffffu); else Tt[tt * 17 + lane] = acc; }
.LBB0_511:
	v_mov_b32_e32 v23, v153

; __device__ __forceinline__ unsigned pk2n(float lo, float hi) { return __builtin_bit_cast(unsigned, __builtin_convertvector((f32x2){lo, hi}, bf16v2)); }
; __device__ __forceinline__ void chunkprep_phase(const Params& P, LAS unsigned char* lds) {
;     ...
;                 for (int tt = 0; tt < 16; ++tt) {
;                     float acc = (pass < 2) ? be[tt] * Kf[tt * 132 + col] : ((tt == lane) ? 1.f : 0.f);
; #pragma unroll
;                     for (int s = 0; s < tt; ++s) acc -= Am[tt * 16 + s] * x[s];
;                     x[tt] = acc;
;                     if (pass < 2) Wb[tt * 136 + col] = (bf16_t)(pk2n(acc, 0.f) & 0xffffu); else Tt[tt * 17 + lane] = acc; }
.LBB0_515:
	v_mov_b32_e32 v24, v154

; __device__ __forceinline__ unsigned pk2n(float lo, float hi) { return __builtin_bit_cast(unsigned, __builtin_convertvector((f32x2){lo, hi}, bf16v2)); }
; __device__ __forceinline__ void chunkprep_phase(const Params& P, LAS unsigned char* lds) {
;     ...
;                 for (int tt = 0; tt < 16; ++tt) {
;                     float acc = (pass < 2) ? be[tt] * Kf[tt * 132 + col] : ((tt == lane) ? 1.f : 0.f);
; #pragma unroll
;                     for (int s = 0; s < tt; ++s) acc -= Am[tt * 16 + s] * x[s];
;                     x[tt] = acc;
;                     if (pass < 2) Wb[tt * 136 + col] = (bf16_t)(pk2n(acc, 0.f) & 0xffffu); else Tt[tt * 17 + lane] = acc; }
.LBB0_519:
	v_mov_b32_e32 v25, v155

; __device__ __forceinline__ unsigned pk2n(float lo, float hi) { return __builtin_bit_cast(unsigned, __builtin_convertvector((f32x2){lo, hi}, bf16v2)); }
; __device__ __forceinline__ void chunkprep_phase(const Params& P, LAS unsigned char* lds) {
;     ...
;                 for (int tt = 0; tt < 16; ++tt) {
;                     float acc = (pass < 2) ? be[tt] * Kf[tt * 132 + col] : ((tt == lane) ? 1.f : 0.f);
; #pragma unroll
;                     for (int s = 0; s < tt; ++s) acc -= Am[tt * 16 + s] * x[s];
;                     x[tt] = acc;
;                     if (pass < 2) Wb[tt * 136 + col] = (bf16_t)(pk2n(acc, 0.f) & 0xffffu); else Tt[tt * 17 + lane] = acc; }
.LBB0_523:
	v_mov_b32_e32 v26, v156

; __device__ __forceinline__ unsigned pk2n(float lo, float hi) { return __builtin_bit_cast(unsigned, __builtin_convertvector((f32x2){lo, hi}, bf16v2)); }
; __device__ __forceinline__ void chunkprep_phase(const Params& P, LAS unsigned char* lds) {
;     ...
;                 for (int tt = 0; tt < 16; ++tt) {
;                     float acc = (pass < 2) ? be[tt] * Kf[tt * 132 + col] : ((tt == lane) ? 1.f : 0.f);
; #pragma unroll
;                     for (int s = 0; s < tt; ++s) acc -= Am[tt * 16 + s] * x[s];
;                     x[tt] = acc;
;                     if (pass < 2) Wb[tt * 136 + col] = (bf16_t)(pk2n(acc, 0.f) & 0xffffu); else Tt[tt * 17 + lane] = acc; }
.LBB0_527:
	v_mov_b32_e32 v27, v157
